# prologue x->out copy: 8 loads in flight per lane then 8 stores (was load->wait->store x32 serial); on top of v32
# speedup vs baseline: 1.0076x; 1.0076x over previous
; __device__ __forceinline__ void prologue(CParams& p, float* smf) {
;     ...
;         const f32x4* s = (const f32x4*)p.x; f32x4* d = (f32x4*)p.out;
;         for (size_t i = gtid; i < (size_t)ML * D / 4; i += gsz) d[i] = s[i];
.LBB0_14:
	s_mov_b64 s[8:9], s[62:63]
	s_cmp_lg_u32 s0, 12
	v_writelane_b32 v248, s8, 24
	s_nop 1
	v_writelane_b32 v248, s9, 25
	s_cbranch_scc1 .LBB0_75
	s_waitcnt vmcnt(27)
	v_mov_b32_e32 v2, v167
	s_mov_b32 s22, s0
	s_mov_b64 s[0:1], s[8:9]
	s_load_dwordx2 s[8:9], s[8:9], 0x0
	v_ashrrev_i32_e32 v3, 31, v2
	v_lshl_add_u64 v[6:7], s[68:69], 0, v[2:3]
	s_mov_b64 s[4:5], 0x400000
	v_cmp_gt_u64_e32 vcc, s[4:5], v[6:7]
	v_readlane_b32 s4, v249, 31
	v_readlane_b32 s5, v249, 32
	s_nop 1
	v_lshl_add_u64 v[0:1], v[2:3], 4, s[4:5]
	s_and_saveexec_b64 s[4:5], vcc
	s_cbranch_execz .LBB0_18
	v_readlane_b32 s6, v249, 31
	v_readlane_b32 s7, v249, 32
	v_mov_b64_e32 v[8:9], v[6:7]
	s_nop 0
	v_lshl_add_u64 v[4:5], v[2:3], 4, s[6:7]
	s_mov_b64 s[6:7], 0
	s_load_dwordx2 s[12:13], s[0:1], 0xc8
	s_lshl_b64 s[44:45], s[70:71], 3
	s_sub_u32 s14, s44, s70
	s_subb_u32 s15, s45, s71
	s_mov_b64 s[16:17], exec
	s_mov_b64 s[42:43], 0x3fffff
.Lpro_cp8:
	v_lshl_add_u64 v[10:11], v[8:9], 0, s[14:15]
	v_cmp_ge_u64_e32 vcc, s[42:43], v[10:11]
	s_nop 1
	s_and_b64 exec, exec, vcc
	s_cbranch_execz .Lpro_cp8_done
	v_mov_b64_e32 v[12:13], v[4:5]
	s_waitcnt lgkmcnt(0)
	v_lshl_add_u64 v[10:11], s[8:9], 0, v[4:5]
	global_load_dwordx4 v[48:51], v[10:11], off
	v_lshl_add_u64 v[4:5], v[4:5], 0, s[60:61]
	v_lshl_add_u64 v[10:11], s[8:9], 0, v[4:5]
	global_load_dwordx4 v[52:55], v[10:11], off
	v_lshl_add_u64 v[4:5], v[4:5], 0, s[60:61]
	v_lshl_add_u64 v[10:11], s[8:9], 0, v[4:5]
	global_load_dwordx4 v[56:59], v[10:11], off
	v_lshl_add_u64 v[4:5], v[4:5], 0, s[60:61]
	v_lshl_add_u64 v[10:11], s[8:9], 0, v[4:5]
	global_load_dwordx4 v[60:63], v[10:11], off
	v_lshl_add_u64 v[4:5], v[4:5], 0, s[60:61]
	v_lshl_add_u64 v[10:11], s[8:9], 0, v[4:5]
	global_load_dwordx4 v[64:67], v[10:11], off
	v_lshl_add_u64 v[4:5], v[4:5], 0, s[60:61]
	v_lshl_add_u64 v[10:11], s[8:9], 0, v[4:5]
	global_load_dwordx4 v[68:71], v[10:11], off
	v_lshl_add_u64 v[4:5], v[4:5], 0, s[60:61]
	v_lshl_add_u64 v[10:11], s[8:9], 0, v[4:5]
	global_load_dwordx4 v[72:75], v[10:11], off
	v_lshl_add_u64 v[4:5], v[4:5], 0, s[60:61]
	v_lshl_add_u64 v[10:11], s[8:9], 0, v[4:5]
	global_load_dwordx4 v[76:79], v[10:11], off
	v_lshl_add_u64 v[4:5], v[4:5], 0, s[60:61]
	s_waitcnt vmcnt(0)
	v_lshl_add_u64 v[10:11], s[12:13], 0, v[12:13]
	global_store_dwordx4 v[10:11], v[48:51], off
	v_lshl_add_u64 v[12:13], v[12:13], 0, s[60:61]
	v_lshl_add_u64 v[10:11], s[12:13], 0, v[12:13]
	global_store_dwordx4 v[10:11], v[52:55], off
	v_lshl_add_u64 v[12:13], v[12:13], 0, s[60:61]
	v_lshl_add_u64 v[10:11], s[12:13], 0, v[12:13]
	global_store_dwordx4 v[10:11], v[56:59], off
	v_lshl_add_u64 v[12:13], v[12:13], 0, s[60:61]
	v_lshl_add_u64 v[10:11], s[12:13], 0, v[12:13]
	global_store_dwordx4 v[10:11], v[60:63], off
	v_lshl_add_u64 v[12:13], v[12:13], 0, s[60:61]
	v_lshl_add_u64 v[10:11], s[12:13], 0, v[12:13]
	global_store_dwordx4 v[10:11], v[64:67], off
	v_lshl_add_u64 v[12:13], v[12:13], 0, s[60:61]
	v_lshl_add_u64 v[10:11], s[12:13], 0, v[12:13]
	global_store_dwordx4 v[10:11], v[68:71], off
	v_lshl_add_u64 v[12:13], v[12:13], 0, s[60:61]
	v_lshl_add_u64 v[10:11], s[12:13], 0, v[12:13]
	global_store_dwordx4 v[10:11], v[72:75], off
	v_lshl_add_u64 v[12:13], v[12:13], 0, s[60:61]
	v_lshl_add_u64 v[10:11], s[12:13], 0, v[12:13]
	global_store_dwordx4 v[10:11], v[76:79], off
	v_lshl_add_u64 v[12:13], v[12:13], 0, s[60:61]
	v_lshl_add_u64 v[8:9], v[8:9], 0, s[44:45]
	s_branch .Lpro_cp8
.Lpro_cp8_done:
	s_mov_b64 exec, s[16:17]
	v_cmp_ge_u64_e32 vcc, s[42:43], v[8:9]
	s_nop 1
	s_and_b64 exec, exec, vcc
	s_cbranch_execz .LBB0_18
